# LayerNorm wave_sum: xor 1,2,4,8 steps via DPP instead of ds_bpermute (32 of 48 LDS round trips per 4 rows removed)
# speedup vs baseline: 1.0068x; 1.0068x over previous
; __device__ __forceinline__ float wave_sum(float v) {
; #pragma unroll
;     for (int o = 1; o < 64; o <<= 1) v += __shfl_xor(v, o);
;     return v;
; __device__ __forceinline__ void ln_pass(h16* Y16, const float* g, const float* b) {
;     ...
;     for (int row0 = (blockIdx.x * 8 + wave) * 4; row0 < NTOK; row0 += gridDim.x * 32) {
;         h16x8 w[4][2];
; #pragma unroll
;         for (int r = 0; r < 4; ++r)
; #pragma unroll
;             for (int j = 0; j < 2; ++j) w[r][j] = *(const h16x8*)(Y16 + (size_t)(row0 + r) * DM + 8 * lane + 512 * j);
; #pragma unroll
;         for (int r = 0; r < 4; ++r) {
;             h16* yr = Y16 + (size_t)(row0 + r) * DM + 8 * lane; f32x4 v[4]; float s = 0.f;
; #pragma unroll
;             for (int j = 0; j < 2; ++j) {
;                 v[2 * j] = (f32x4){(float)w[r][j][0], (float)w[r][j][1], (float)w[r][j][2], (float)w[r][j][3]}; v[2 * j + 1] = (f32x4){(float)w[r][j][4], (float)w[r][j][5], (float)w[r][j][6], (float)w[r][j][7]}; }
; #pragma unroll
;             for (int j = 0; j < 4; ++j) s += (v[j].x + v[j].y) + (v[j].z + v[j].w);
;             const float mean = wave_sum(s) * (1.f / DM); float s2 = 0.f;
; #pragma unroll
;             for (int j = 0; j < 4; ++j) { v[j] = v[j] - mean; s2 += (v[j].x * v[j].x + v[j].y * v[j].y) + (v[j].z * v[j].z + v[j].w * v[j].w); }
;             const float rstd = 1.f / sqrtf(wave_sum(s2) * (1.f / DM) + LN_EPS);
.LBB0_1063:
	v_ashrrev_i32_e32 v57, 31, v56
	v_lshlrev_b64 v[32:33], 11, v[56:57]
	v_lshl_add_u64 v[70:71], v[58:59], 0, v[32:33]
	global_load_dwordx4 v[66:69], v[70:71], off
	global_load_dwordx4 v[78:81], v[70:71], off offset:1024
	v_add_u32_e32 v32, 1, v56
	v_ashrrev_i32_e32 v33, 31, v32
	v_lshlrev_b64 v[32:33], 11, v[32:33]
	v_lshl_add_u64 v[64:65], v[58:59], 0, v[32:33]
	global_load_dwordx4 v[52:55], v[64:65], off
	global_load_dwordx4 v[48:51], v[64:65], off offset:1024
	v_add_u32_e32 v32, 2, v56
	v_ashrrev_i32_e32 v33, 31, v32
	v_lshlrev_b64 v[32:33], 11, v[32:33]
	v_lshl_add_u64 v[62:63], v[58:59], 0, v[32:33]
	v_add_u32_e32 v32, 3, v56
	v_ashrrev_i32_e32 v33, 31, v32
	v_lshlrev_b64 v[32:33], 11, v[32:33]
	v_lshl_add_u64 v[60:61], v[58:59], 0, v[32:33]
	global_load_dwordx4 v[44:47], v[62:63], off
	global_load_dwordx4 v[40:43], v[62:63], off offset:1024
	global_load_dwordx4 v[36:39], v[60:61], off
	global_load_dwordx4 v[32:35], v[60:61], off offset:1024
	v_add_u32_e32 v56, s69, v56
	s_waitcnt vmcnt(7)
	v_cvt_f32_f16_e32 v82, v66
	v_cvt_f32_f16_sdwa v84, v66 dst_sel:DWORD dst_unused:UNUSED_PAD src0_sel:WORD_1
	v_cvt_f32_f16_e32 v83, v67
	v_cvt_f32_f16_sdwa v85, v67 dst_sel:DWORD dst_unused:UNUSED_PAD src0_sel:WORD_1
	v_cvt_f32_f16_e32 v86, v68
	v_cvt_f32_f16_sdwa v88, v68 dst_sel:DWORD dst_unused:UNUSED_PAD src0_sel:WORD_1
	v_cvt_f32_f16_e32 v87, v69
	v_cvt_f32_f16_sdwa v89, v69 dst_sel:DWORD dst_unused:UNUSED_PAD src0_sel:WORD_1
	s_waitcnt vmcnt(6)
	v_cvt_f32_f16_e32 v57, v78
	v_cvt_f32_f16_sdwa v91, v78 dst_sel:DWORD dst_unused:UNUSED_PAD src0_sel:WORD_1
	v_cvt_f32_f16_e32 v93, v79
	v_cvt_f32_f16_sdwa v97, v79 dst_sel:DWORD dst_unused:UNUSED_PAD src0_sel:WORD_1
	v_pk_add_f32 v[82:83], v[82:83], v[84:85]
	v_cvt_f32_f16_e32 v90, v80
	v_cvt_f32_f16_sdwa v92, v80 dst_sel:DWORD dst_unused:UNUSED_PAD src0_sel:WORD_1
	v_cvt_f32_f16_sdwa v94, v81 dst_sel:DWORD dst_unused:UNUSED_PAD src0_sel:WORD_1
	v_cvt_f32_f16_e32 v96, v81
	v_add_f32_e32 v82, v82, v83
	v_add_f32_e32 v95, 0, v82
	v_pk_add_f32 v[82:83], v[86:87], v[88:89]
	v_add_f32_e32 v91, v57, v91
	v_pk_add_f32 v[82:83], v[82:83], v[82:83] op_sel_hi:[0,1]
	v_add_f32_e32 v93, v93, v97
	v_mov_b32_e32 v97, v83
	v_pk_add_f32 v[84:85], v[90:91], v[92:93]
	v_pk_add_f32 v[82:83], v[96:97], v[94:95]
	s_nop 0
	v_pk_add_f32 v[82:83], v[84:85], v[82:83]
	s_nop 0
	v_add_f32_e32 v57, v82, v83
	s_nop 1
	v_mov_b32_dpp v82, v57 quad_perm:[1,0,3,2] row_mask:0xf bank_mask:0xf
	s_waitcnt lgkmcnt(0)
	v_add_f32_e32 v57, v57, v82
	s_nop 1
	v_mov_b32_dpp v82, v57 quad_perm:[2,3,0,1] row_mask:0xf bank_mask:0xf
	s_waitcnt lgkmcnt(0)
	v_add_f32_e32 v57, v57, v82
	s_nop 1
	v_mov_b32_dpp v82, v57 row_ror:4 row_mask:0xf bank_mask:0xf
	s_waitcnt lgkmcnt(0)
	v_add_f32_e32 v57, v57, v82
	s_nop 1
	v_mov_b32_dpp v82, v57 row_ror:8 row_mask:0xf bank_mask:0xf
	s_waitcnt lgkmcnt(0)
	v_add_f32_e32 v57, v57, v82
	ds_bpermute_b32 v82, v76, v57
	s_waitcnt lgkmcnt(0)
	v_add_f32_e32 v57, v57, v82
	ds_bpermute_b32 v82, v77, v57
	s_waitcnt lgkmcnt(0)
	v_add_f32_e32 v57, v57, v82
	v_fma_mix_f32 v83, v57, s73, v66 op_sel:[0,0,1] op_sel_hi:[0,0,1]
	v_fma_mix_f32 v82, v57, s73, v66 op_sel_hi:[0,0,1]
	v_fma_mix_f32 v85, v57, s73, v67 op_sel:[0,0,1] op_sel_hi:[0,0,1]
	v_fma_mix_f32 v84, v57, s73, v67 op_sel_hi:[0,0,1]
	v_pk_mul_f32 v[66:67], v[84:85], v[84:85]
	v_pk_mul_f32 v[86:87], v[82:83], v[82:83]
	v_fma_mix_f32 v97, v57, s73, v81 op_sel:[0,0,1] op_sel_hi:[0,0,1]
	v_pk_mov_b32 v[88:89], v[86:87], v[66:67] op_sel:[1,0]
	v_mov_b32_e32 v87, v67
	v_pk_add_f32 v[66:67], v[88:89], v[86:87]
	v_fma_mix_f32 v87, v57, s73, v68 op_sel:[0,0,1] op_sel_hi:[0,0,1]
	v_fma_mix_f32 v86, v57, s73, v68 op_sel_hi:[0,0,1]
	v_fma_mix_f32 v89, v57, s73, v69 op_sel:[0,0,1] op_sel_hi:[0,0,1]
	v_fma_mix_f32 v88, v57, s73, v69 op_sel_hi:[0,0,1]
	v_pk_mul_f32 v[68:69], v[88:89], v[88:89]
	v_pk_mul_f32 v[90:91], v[86:87], v[86:87]
	v_pk_add_f32 v[66:67], v[66:67], v[66:67] op_sel_hi:[0,1]
	v_pk_mov_b32 v[92:93], v[90:91], v[68:69] op_sel:[1,0]
	v_mov_b32_e32 v91, v69
	v_pk_add_f32 v[68:69], v[92:93], v[90:91]
	v_fma_mix_f32 v90, v57, s73, v78 op_sel_hi:[0,0,1]
	v_fma_mix_f32 v91, v57, s73, v78 op_sel:[0,0,1] op_sel_hi:[0,0,1]
	v_fma_mix_f32 v92, v57, s73, v79 op_sel_hi:[0,0,1]
	v_mul_f32_e32 v66, v90, v90
	v_fma_mix_f32 v93, v57, s73, v79 op_sel:[0,0,1] op_sel_hi:[0,0,1]
	v_pk_fma_f32 v[78:79], v[90:91], v[90:91], v[66:67] op_sel_hi:[1,1,0]
	v_mul_f32_e32 v66, v92, v92
	v_pk_add_f32 v[68:69], v[68:69], v[68:69] op_sel_hi:[0,1]
	v_pk_fma_f32 v[94:95], v[92:93], v[92:93], v[66:67] op_sel_hi:[1,1,0]
	v_fma_mix_f32 v96, v57, s73, v81 op_sel_hi:[0,0,1]
	v_fma_mix_f32 v81, v57, s73, v80 op_sel:[0,0,1] op_sel_hi:[0,0,1]
	v_fma_mix_f32 v80, v57, s73, v80 op_sel_hi:[0,0,1]
	v_mul_f32_e32 v78, v80, v80
	v_mul_f32_e32 v94, v81, v81
	v_mul_f32_e32 v66, v96, v96
	v_mul_f32_e32 v68, v97, v97
	v_pk_add_f32 v[78:79], v[78:79], v[94:95]
	v_pk_add_f32 v[66:67], v[66:67], v[68:69]
	s_nop 0
	v_pk_add_f32 v[66:67], v[78:79], v[66:67]
	s_nop 0
	v_add_f32_e32 v57, v66, v67
	s_nop 1
	v_mov_b32_dpp v66, v57 quad_perm:[1,0,3,2] row_mask:0xf bank_mask:0xf
	s_waitcnt lgkmcnt(0)
	v_add_f32_e32 v57, v57, v66
	s_nop 1
	v_mov_b32_dpp v66, v57 quad_perm:[2,3,0,1] row_mask:0xf bank_mask:0xf
	s_waitcnt lgkmcnt(0)
	v_add_f32_e32 v57, v57, v66
	s_nop 1
	v_mov_b32_dpp v66, v57 row_ror:4 row_mask:0xf bank_mask:0xf
	s_waitcnt lgkmcnt(0)
	v_add_f32_e32 v57, v57, v66
	s_nop 1
	v_mov_b32_dpp v66, v57 row_ror:8 row_mask:0xf bank_mask:0xf
	s_waitcnt lgkmcnt(0)
	v_add_f32_e32 v57, v57, v66
	ds_bpermute_b32 v66, v76, v57
	s_waitcnt lgkmcnt(0)
	v_add_f32_e32 v57, v57, v66
	ds_bpermute_b32 v66, v77, v57
	s_waitcnt lgkmcnt(0)
; __device__ __forceinline__ float wave_sum(float v) {
; #pragma unroll
;     for (int o = 1; o < 64; o <<= 1) v += __shfl_xor(v, o);
;     return v;
; __device__ __forceinline__ void ln_pass(h16* Y16, const float* g, const float* b) {
;     ...
;             const float mean = wave_sum(s) * (1.f / DM); float s2 = 0.f;
; #pragma unroll
;             for (int j = 0; j < 4; ++j) { v[j] = v[j] - mean; s2 += (v[j].x * v[j].x + v[j].y * v[j].y) + (v[j].z * v[j].z + v[j].w * v[j].w); }
;             const float rstd = 1.f / sqrtf(wave_sum(s2) * (1.f / DM) + LN_EPS);
; #pragma unroll
;             for (int j = 0; j < 2; ++j) { const f32x4 o0 = v[2 * j] * rstd * gv[2 * j] + bv[2 * j], o1 = v[2 * j + 1] * rstd * gv[2 * j + 1] + bv[2 * j + 1]; h16x8 o;
;                 o[0] = (h16)o0.x; o[1] = (h16)o0.y; o[2] = (h16)o0.z; o[3] = (h16)o0.w; o[4] = (h16)o1.x; o[5] = (h16)o1.y; o[6] = (h16)o1.z; o[7] = (h16)o1.w;
;                 *(h16x8*)(yr + 512 * j) = o; }
	v_add_f32_e32 v57, v57, v66
	v_fmamk_f32 v57, v57, 0x3a800000, v213
	v_cmp_gt_f32_e32 vcc, s52, v57
	v_mul_f32_e32 v66, 0x4f800000, v57
	s_nop 0
	v_cndmask_b32_e32 v57, v57, v66, vcc
	v_sqrt_f32_e32 v66, v57
	s_nop 0
	v_add_u32_e32 v67, -1, v66
	v_fma_f32 v68, -v67, v66, v57
	v_cmp_ge_f32_e64 s[10:11], 0, v68
	v_add_u32_e32 v68, 1, v66
	s_nop 0
	v_cndmask_b32_e64 v67, v66, v67, s[10:11]
	v_fma_f32 v66, -v68, v66, v57
	v_cmp_lt_f32_e64 s[10:11], 0, v66
	s_nop 1
	v_cndmask_b32_e64 v66, v67, v68, s[10:11]
	v_mul_f32_e32 v67, 0x37800000, v66
	v_cndmask_b32_e32 v66, v66, v67, vcc
	v_cmp_class_f32_e32 vcc, v57, v214
	s_nop 1
	v_cndmask_b32_e32 v57, v66, v57, vcc
	v_div_scale_f32 v66, s[10:11], v57, v57, 1.0
	v_rcp_f32_e32 v67, v66
	s_nop 0
	v_fma_f32 v68, -v66, v67, 1.0
	v_fmac_f32_e32 v67, v68, v67
	v_div_scale_f32 v68, vcc, 1.0, v57, 1.0
	v_mul_f32_e32 v69, v68, v67
	v_fma_f32 v78, -v66, v69, v68
	v_fmac_f32_e32 v69, v78, v67
	v_fma_f32 v66, -v66, v69, v68
	v_div_fmas_f32 v66, v66, v67, v69
	v_div_fixup_f32 v78, v66, v57, 1.0
	v_pk_mul_f32 v[66:67], v[82:83], v[78:79] op_sel_hi:[1,0]
	v_pk_mul_f32 v[68:69], v[84:85], v[78:79] op_sel_hi:[1,0]
	v_pk_fma_f32 v[84:85], v[4:5], v[66:67], v[12:13]
	v_pk_fma_f32 v[82:83], v[6:7], v[68:69], v[14:15]
	v_pk_mul_f32 v[66:67], v[86:87], v[78:79] op_sel_hi:[1,0]
	v_pk_mul_f32 v[68:69], v[88:89], v[78:79] op_sel_hi:[1,0]
	v_pk_fma_f32 v[66:67], v[0:1], v[66:67], v[8:9]
	v_pk_fma_f32 v[68:69], v[2:3], v[68:69], v[10:11]
	s_waitcnt vmcnt(4)
	v_cvt_f32_f16_e32 v57, v48
	v_cvt_pk_f16_f32 v69, v68, v69
	v_cvt_pk_f16_f32 v68, v66, v67
	v_cvt_pk_f16_f32 v67, v82, v83
	v_cvt_pk_f16_f32 v66, v84, v85
	global_store_dwordx4 v[70:71], v[66:69], off
	v_cvt_f32_f16_sdwa v87, v49 dst_sel:DWORD dst_unused:UNUSED_PAD src0_sel:WORD_1
	v_cvt_f32_f16_e32 v86, v51
	v_pk_mul_f32 v[66:67], v[90:91], v[78:79] op_sel_hi:[1,0]
	v_pk_mul_f32 v[68:69], v[92:93], v[78:79] op_sel_hi:[1,0]
	v_pk_fma_f32 v[84:85], v[20:21], v[66:67], v[28:29]
	v_pk_fma_f32 v[82:83], v[22:23], v[68:69], v[30:31]
	v_pk_mul_f32 v[66:67], v[80:81], v[78:79] op_sel_hi:[1,0]
	v_pk_mul_f32 v[68:69], v[96:97], v[78:79] op_sel_hi:[1,0]
	v_pk_fma_f32 v[66:67], v[16:17], v[66:67], v[24:25]
	v_pk_fma_f32 v[68:69], v[18:19], v[68:69], v[26:27]
	v_cvt_f32_f16_sdwa v78, v54 dst_sel:DWORD dst_unused:UNUSED_PAD src0_sel:WORD_1
	v_cvt_pk_f16_f32 v69, v68, v69
	v_cvt_pk_f16_f32 v68, v66, v67
	v_cvt_pk_f16_f32 v67, v82, v83
	v_cvt_pk_f16_f32 v66, v84, v85
	global_store_dwordx4 v[70:71], v[66:69], off offset:1024
	v_cvt_f32_f16_e32 v70, v54
	v_cvt_f32_f16_e32 v71, v55
	v_cvt_f32_f16_e32 v66, v52
	v_cvt_f32_f16_sdwa v68, v52 dst_sel:DWORD dst_unused:UNUSED_PAD src0_sel:WORD_1
	v_cvt_f32_f16_e32 v67, v53
	v_cvt_f32_f16_sdwa v69, v53 dst_sel:DWORD dst_unused:UNUSED_PAD src0_sel:WORD_1
	v_cvt_f32_f16_sdwa v79, v55 dst_sel:DWORD dst_unused:UNUSED_PAD src0_sel:WORD_1
	v_cvt_f32_f16_sdwa v81, v48 dst_sel:DWORD dst_unused:UNUSED_PAD src0_sel:WORD_1
	v_cvt_f32_f16_e32 v83, v49
	v_pk_add_f32 v[66:67], v[66:67], v[68:69]
	v_cvt_f32_f16_e32 v80, v50
	v_cvt_f32_f16_sdwa v82, v50 dst_sel:DWORD dst_unused:UNUSED_PAD src0_sel:WORD_1
	v_cvt_f32_f16_sdwa v84, v51 dst_sel:DWORD dst_unused:UNUSED_PAD src0_sel:WORD_1
	v_add_f32_e32 v66, v66, v67
	v_add_f32_e32 v85, 0, v66
	v_pk_add_f32 v[66:67], v[70:71], v[78:79]
	v_add_f32_e32 v81, v57, v81
	v_pk_add_f32 v[66:67], v[66:67], v[66:67] op_sel_hi:[0,1]
	v_add_f32_e32 v83, v83, v87
	v_mov_b32_e32 v87, v67
	v_pk_add_f32 v[68:69], v[80:81], v[82:83]
	v_pk_add_f32 v[66:67], v[86:87], v[84:85]
	s_nop 0
	v_pk_add_f32 v[66:67], v[68:69], v[66:67]
	s_nop 0
	v_add_f32_e32 v57, v66, v67
	s_nop 1
	v_mov_b32_dpp v66, v57 quad_perm:[1,0,3,2] row_mask:0xf bank_mask:0xf
	s_waitcnt lgkmcnt(0)
	v_add_f32_e32 v57, v57, v66
	s_nop 1
	v_mov_b32_dpp v66, v57 quad_perm:[2,3,0,1] row_mask:0xf bank_mask:0xf
	s_waitcnt lgkmcnt(0)
	v_add_f32_e32 v57, v57, v66
	s_nop 1
	v_mov_b32_dpp v66, v57 row_ror:4 row_mask:0xf bank_mask:0xf
	s_waitcnt lgkmcnt(0)
	v_add_f32_e32 v57, v57, v66
	s_nop 1
	v_mov_b32_dpp v66, v57 row_ror:8 row_mask:0xf bank_mask:0xf
	s_waitcnt lgkmcnt(0)
	v_add_f32_e32 v57, v57, v66
	ds_bpermute_b32 v66, v76, v57
	s_waitcnt lgkmcnt(0)
	v_add_f32_e32 v57, v57, v66
	ds_bpermute_b32 v66, v77, v57
	s_waitcnt lgkmcnt(0)
	v_add_f32_e32 v57, v57, v66
	v_fma_mix_f32 v67, v57, s73, v52 op_sel:[0,0,1] op_sel_hi:[0,0,1]
	v_fma_mix_f32 v66, v57, s73, v52 op_sel_hi:[0,0,1]
	v_fma_mix_f32 v69, v57, s73, v53 op_sel:[0,0,1] op_sel_hi:[0,0,1]
	v_fma_mix_f32 v68, v57, s73, v53 op_sel_hi:[0,0,1]
	v_pk_mul_f32 v[52:53], v[68:69], v[68:69]
	v_pk_mul_f32 v[70:71], v[66:67], v[66:67]
	v_fma_mix_f32 v87, v57, s73, v51 op_sel:[0,0,1] op_sel_hi:[0,0,1]
	v_pk_mov_b32 v[78:79], v[70:71], v[52:53] op_sel:[1,0]
	v_mov_b32_e32 v71, v53
	v_pk_add_f32 v[52:53], v[78:79], v[70:71]
	v_fma_mix_f32 v71, v57, s73, v55 op_sel:[0,0,1] op_sel_hi:[0,0,1]
	v_pk_add_f32 v[78:79], v[52:53], v[52:53] op_sel_hi:[0,1]
	v_fma_mix_f32 v53, v57, s73, v54 op_sel:[0,0,1] op_sel_hi:[0,0,1]
	v_fma_mix_f32 v52, v57, s73, v54 op_sel_hi:[0,0,1]
	v_fma_mix_f32 v70, v57, s73, v55 op_sel_hi:[0,0,1]
	v_pk_mul_f32 v[54:55], v[70:71], v[70:71]
	v_pk_mul_f32 v[80:81], v[52:53], v[52:53]
	v_fma_mix_f32 v86, v57, s73, v51 op_sel_hi:[0,0,1]
	v_pk_mov_b32 v[82:83], v[80:81], v[54:55] op_sel:[1,0]
	v_mov_b32_e32 v81, v55
	v_pk_add_f32 v[54:55], v[82:83], v[80:81]
	v_fma_mix_f32 v80, v57, s73, v48 op_sel_hi:[0,0,1]
	v_fma_mix_f32 v81, v57, s73, v48 op_sel:[0,0,1] op_sel_hi:[0,0,1]
	v_mul_f32_e32 v48, v80, v80
	v_fma_mix_f32 v83, v57, s73, v49 op_sel:[0,0,1] op_sel_hi:[0,0,1]
	v_fma_mix_f32 v82, v57, s73, v49 op_sel_hi:[0,0,1]
	v_pk_fma_f32 v[48:49], v[80:81], v[80:81], v[48:49] op_sel_hi:[1,1,0]
	v_pk_add_f32 v[54:55], v[54:55], v[54:55] op_sel_hi:[0,1]
	v_mul_f32_e32 v48, v82, v82
	v_pk_fma_f32 v[84:85], v[82:83], v[82:83], v[48:49] op_sel_hi:[1,1,0]
	v_fma_mix_f32 v89, v57, s73, v50 op_sel:[0,0,1] op_sel_hi:[0,0,1]
	v_fma_mix_f32 v88, v57, s73, v50 op_sel_hi:[0,0,1]
	v_mul_f32_e32 v48, v88, v88
	v_mul_f32_e32 v84, v89, v89
	v_mul_f32_e32 v78, v86, v86
	v_mul_f32_e32 v54, v87, v87
	v_pk_add_f32 v[48:49], v[48:49], v[84:85]
	v_pk_add_f32 v[50:51], v[78:79], v[54:55]
	s_waitcnt vmcnt(4)
; __device__ __forceinline__ float wave_sum(float v) {
; #pragma unroll
;     for (int o = 1; o < 64; o <<= 1) v += __shfl_xor(v, o);
;     return v;
; __device__ __forceinline__ void ln_pass(h16* Y16, const float* g, const float* b) {
;     ...
;             const float mean = wave_sum(s) * (1.f / DM); float s2 = 0.f;
; #pragma unroll
;             for (int j = 0; j < 4; ++j) { v[j] = v[j] - mean; s2 += (v[j].x * v[j].x + v[j].y * v[j].y) + (v[j].z * v[j].z + v[j].w * v[j].w); }
;             const float rstd = 1.f / sqrtf(wave_sum(s2) * (1.f / DM) + LN_EPS);
; #pragma unroll
;             for (int j = 0; j < 2; ++j) { const f32x4 o0 = v[2 * j] * rstd * gv[2 * j] + bv[2 * j], o1 = v[2 * j + 1] * rstd * gv[2 * j + 1] + bv[2 * j + 1]; h16x8 o;
;                 o[0] = (h16)o0.x; o[1] = (h16)o0.y; o[2] = (h16)o0.z; o[3] = (h16)o0.w; o[4] = (h16)o1.x; o[5] = (h16)o1.y; o[6] = (h16)o1.z; o[7] = (h16)o1.w;
;                 *(h16x8*)(yr + 512 * j) = o; }
	v_cvt_f32_f16_e32 v57, v40
	v_pk_add_f32 v[48:49], v[48:49], v[50:51]
	s_nop 0
	v_add_f32_e32 v48, v48, v49
	s_nop 1
	v_mov_b32_dpp v49, v48 quad_perm:[1,0,3,2] row_mask:0xf bank_mask:0xf
	s_waitcnt lgkmcnt(0)
	v_add_f32_e32 v48, v48, v49
	s_nop 1
	v_mov_b32_dpp v49, v48 quad_perm:[2,3,0,1] row_mask:0xf bank_mask:0xf
	s_waitcnt lgkmcnt(0)
	v_add_f32_e32 v48, v48, v49
	s_nop 1
	v_mov_b32_dpp v49, v48 row_ror:4 row_mask:0xf bank_mask:0xf
	s_waitcnt lgkmcnt(0)
	v_add_f32_e32 v48, v48, v49
	s_nop 1
	v_mov_b32_dpp v49, v48 row_ror:8 row_mask:0xf bank_mask:0xf
	s_waitcnt lgkmcnt(0)
	v_add_f32_e32 v48, v48, v49
	ds_bpermute_b32 v49, v76, v48
	s_waitcnt lgkmcnt(0)
	v_add_f32_e32 v48, v48, v49
	ds_bpermute_b32 v49, v77, v48
	s_waitcnt lgkmcnt(0)
	v_add_f32_e32 v48, v48, v49
	v_fmamk_f32 v48, v48, 0x3a800000, v213
	v_cmp_gt_f32_e32 vcc, s52, v48
	v_mul_f32_e32 v49, 0x4f800000, v48
	s_nop 0
	v_cndmask_b32_e32 v48, v48, v49, vcc
	v_sqrt_f32_e32 v49, v48
	s_nop 0
	v_add_u32_e32 v50, -1, v49
	v_fma_f32 v51, -v50, v49, v48
	v_cmp_ge_f32_e64 s[10:11], 0, v51
	v_add_u32_e32 v51, 1, v49
	s_nop 0
	v_cndmask_b32_e64 v50, v49, v50, s[10:11]
	v_fma_f32 v49, -v51, v49, v48
	v_cmp_lt_f32_e64 s[10:11], 0, v49
	s_nop 1
	v_cndmask_b32_e64 v49, v50, v51, s[10:11]
	v_mul_f32_e32 v50, 0x37800000, v49
	v_cndmask_b32_e32 v49, v49, v50, vcc
	v_cmp_class_f32_e32 vcc, v48, v214
	s_nop 1
	v_cndmask_b32_e32 v48, v49, v48, vcc
	v_div_scale_f32 v49, s[10:11], v48, v48, 1.0
	v_rcp_f32_e32 v50, v49
	s_nop 0
	v_fma_f32 v51, -v49, v50, 1.0
	v_fmac_f32_e32 v50, v51, v50
	v_div_scale_f32 v51, vcc, 1.0, v48, 1.0
	v_mul_f32_e32 v54, v51, v50
	v_fma_f32 v55, -v49, v54, v51
	v_fmac_f32_e32 v54, v55, v50
	v_fma_f32 v49, -v49, v54, v51
	v_div_fmas_f32 v49, v49, v50, v54
	v_div_fixup_f32 v54, v49, v48, 1.0
	v_pk_mul_f32 v[48:49], v[66:67], v[54:55] op_sel_hi:[1,0]
	v_pk_mul_f32 v[50:51], v[68:69], v[54:55] op_sel_hi:[1,0]
	v_pk_fma_f32 v[68:69], v[4:5], v[48:49], v[12:13]
	v_pk_fma_f32 v[66:67], v[6:7], v[50:51], v[14:15]
	v_pk_mul_f32 v[48:49], v[52:53], v[54:55] op_sel_hi:[1,0]
	v_pk_mul_f32 v[50:51], v[70:71], v[54:55] op_sel_hi:[1,0]
	v_pk_fma_f32 v[48:49], v[0:1], v[48:49], v[8:9]
	v_pk_fma_f32 v[50:51], v[2:3], v[50:51], v[10:11]
	v_cvt_f32_f16_sdwa v71, v41 dst_sel:DWORD dst_unused:UNUSED_PAD src0_sel:WORD_1
	v_cvt_pk_f16_f32 v51, v50, v51
	v_cvt_pk_f16_f32 v50, v48, v49
	v_cvt_pk_f16_f32 v49, v66, v67
	v_cvt_pk_f16_f32 v48, v68, v69
	global_store_dwordx4 v[64:65], v[48:51], off
	v_cvt_f32_f16_sdwa v68, v43 dst_sel:DWORD dst_unused:UNUSED_PAD src0_sel:WORD_1
	v_cvt_f32_f16_e32 v70, v43
	v_pk_mul_f32 v[48:49], v[80:81], v[54:55] op_sel_hi:[1,0]
	v_pk_mul_f32 v[50:51], v[82:83], v[54:55] op_sel_hi:[1,0]
	v_pk_fma_f32 v[66:67], v[20:21], v[48:49], v[28:29]
	v_pk_fma_f32 v[52:53], v[22:23], v[50:51], v[30:31]
	v_pk_mul_f32 v[48:49], v[88:89], v[54:55] op_sel_hi:[1,0]
	v_pk_mul_f32 v[50:51], v[86:87], v[54:55] op_sel_hi:[1,0]
	v_pk_fma_f32 v[48:49], v[16:17], v[48:49], v[24:25]
	v_pk_fma_f32 v[50:51], v[18:19], v[50:51], v[26:27]
	v_cvt_f32_f16_sdwa v54, v46 dst_sel:DWORD dst_unused:UNUSED_PAD src0_sel:WORD_1
	v_cvt_pk_f16_f32 v51, v50, v51
	v_cvt_pk_f16_f32 v50, v48, v49
	v_cvt_pk_f16_f32 v49, v52, v53
	v_cvt_pk_f16_f32 v48, v66, v67
	global_store_dwordx4 v[64:65], v[48:51], off offset:1024
	v_cvt_f32_f16_e32 v52, v46
	v_cvt_f32_f16_e32 v53, v47
	v_cvt_f32_f16_e32 v48, v44
	v_cvt_f32_f16_sdwa v50, v44 dst_sel:DWORD dst_unused:UNUSED_PAD src0_sel:WORD_1
	v_cvt_f32_f16_e32 v49, v45
	v_cvt_f32_f16_sdwa v51, v45 dst_sel:DWORD dst_unused:UNUSED_PAD src0_sel:WORD_1
	v_cvt_f32_f16_sdwa v55, v47 dst_sel:DWORD dst_unused:UNUSED_PAD src0_sel:WORD_1
	v_cvt_f32_f16_sdwa v65, v40 dst_sel:DWORD dst_unused:UNUSED_PAD src0_sel:WORD_1
	v_cvt_f32_f16_e32 v67, v41
	v_pk_add_f32 v[48:49], v[48:49], v[50:51]
	v_cvt_f32_f16_e32 v64, v42
	v_cvt_f32_f16_sdwa v66, v42 dst_sel:DWORD dst_unused:UNUSED_PAD src0_sel:WORD_1
	v_add_f32_e32 v48, v48, v49
	v_add_f32_e32 v69, 0, v48
	v_pk_add_f32 v[48:49], v[52:53], v[54:55]
	v_add_f32_e32 v65, v57, v65
	v_pk_add_f32 v[48:49], v[48:49], v[48:49] op_sel_hi:[0,1]
	v_add_f32_e32 v67, v67, v71
	v_mov_b32_e32 v71, v49
	v_pk_add_f32 v[50:51], v[64:65], v[66:67]
	v_pk_add_f32 v[48:49], v[70:71], v[68:69]
	s_nop 0
	v_pk_add_f32 v[48:49], v[50:51], v[48:49]
	s_nop 0
	v_add_f32_e32 v48, v48, v49
	s_nop 1
	v_mov_b32_dpp v49, v48 quad_perm:[1,0,3,2] row_mask:0xf bank_mask:0xf
	s_waitcnt lgkmcnt(0)
	v_add_f32_e32 v48, v48, v49
	s_nop 1
	v_mov_b32_dpp v49, v48 quad_perm:[2,3,0,1] row_mask:0xf bank_mask:0xf
	s_waitcnt lgkmcnt(0)
	v_add_f32_e32 v48, v48, v49
	s_nop 1
	v_mov_b32_dpp v49, v48 row_ror:4 row_mask:0xf bank_mask:0xf
	s_waitcnt lgkmcnt(0)
	v_add_f32_e32 v48, v48, v49
	s_nop 1
	v_mov_b32_dpp v49, v48 row_ror:8 row_mask:0xf bank_mask:0xf
	s_waitcnt lgkmcnt(0)
	v_add_f32_e32 v48, v48, v49
	ds_bpermute_b32 v49, v76, v48
	s_waitcnt lgkmcnt(0)
	v_add_f32_e32 v48, v48, v49
	ds_bpermute_b32 v49, v77, v48
	s_waitcnt lgkmcnt(0)
; __device__ __forceinline__ float wave_sum(float v) {
; #pragma unroll
;     for (int o = 1; o < 64; o <<= 1) v += __shfl_xor(v, o);
;     return v;
; __device__ __forceinline__ void ln_pass(h16* Y16, const float* g, const float* b) {
;     ...
;             const float mean = wave_sum(s) * (1.f / DM); float s2 = 0.f;
; #pragma unroll
;             for (int j = 0; j < 4; ++j) { v[j] = v[j] - mean; s2 += (v[j].x * v[j].x + v[j].y * v[j].y) + (v[j].z * v[j].z + v[j].w * v[j].w); }
;             const float rstd = 1.f / sqrtf(wave_sum(s2) * (1.f / DM) + LN_EPS);
; #pragma unroll
;             for (int j = 0; j < 2; ++j) { const f32x4 o0 = v[2 * j] * rstd * gv[2 * j] + bv[2 * j], o1 = v[2 * j + 1] * rstd * gv[2 * j + 1] + bv[2 * j + 1]; h16x8 o;
;                 o[0] = (h16)o0.x; o[1] = (h16)o0.y; o[2] = (h16)o0.z; o[3] = (h16)o0.w; o[4] = (h16)o1.x; o[5] = (h16)o1.y; o[6] = (h16)o1.z; o[7] = (h16)o1.w;
;                 *(h16x8*)(yr + 512 * j) = o; }
	v_add_f32_e32 v57, v48, v49
	v_fma_mix_f32 v49, v57, s73, v44 op_sel:[0,0,1] op_sel_hi:[0,0,1]
	v_fma_mix_f32 v48, v57, s73, v44 op_sel_hi:[0,0,1]
	v_fma_mix_f32 v51, v57, s73, v45 op_sel:[0,0,1] op_sel_hi:[0,0,1]
	v_fma_mix_f32 v50, v57, s73, v45 op_sel_hi:[0,0,1]
	v_pk_mul_f32 v[44:45], v[50:51], v[50:51]
	v_pk_mul_f32 v[52:53], v[48:49], v[48:49]
	v_fma_mix_f32 v71, v57, s73, v43 op_sel:[0,0,1] op_sel_hi:[0,0,1]
	v_pk_mov_b32 v[54:55], v[52:53], v[44:45] op_sel:[1,0]
	v_mov_b32_e32 v53, v45
	v_pk_add_f32 v[44:45], v[54:55], v[52:53]
	v_fma_mix_f32 v53, v57, s73, v46 op_sel:[0,0,1] op_sel_hi:[0,0,1]
	v_fma_mix_f32 v52, v57, s73, v46 op_sel_hi:[0,0,1]
	v_fma_mix_f32 v55, v57, s73, v47 op_sel:[0,0,1] op_sel_hi:[0,0,1]
	v_fma_mix_f32 v54, v57, s73, v47 op_sel_hi:[0,0,1]
	v_pk_mul_f32 v[46:47], v[54:55], v[54:55]
	v_pk_mul_f32 v[64:65], v[52:53], v[52:53]
	v_pk_add_f32 v[44:45], v[44:45], v[44:45] op_sel_hi:[0,1]
	v_pk_mov_b32 v[66:67], v[64:65], v[46:47] op_sel:[1,0]
	v_mov_b32_e32 v65, v47
	v_pk_add_f32 v[46:47], v[66:67], v[64:65]
	v_fma_mix_f32 v64, v57, s73, v40 op_sel_hi:[0,0,1]
	v_fma_mix_f32 v65, v57, s73, v40 op_sel:[0,0,1] op_sel_hi:[0,0,1]
	v_mul_f32_e32 v40, v64, v64
	v_fma_mix_f32 v67, v57, s73, v41 op_sel:[0,0,1] op_sel_hi:[0,0,1]
	v_fma_mix_f32 v66, v57, s73, v41 op_sel_hi:[0,0,1]
	v_pk_fma_f32 v[40:41], v[64:65], v[64:65], v[40:41] op_sel_hi:[1,1,0]
	v_pk_add_f32 v[46:47], v[46:47], v[46:47] op_sel_hi:[0,1]
	v_mul_f32_e32 v40, v66, v66
	v_pk_fma_f32 v[68:69], v[66:67], v[66:67], v[40:41] op_sel_hi:[1,1,0]
	v_fma_mix_f32 v70, v57, s73, v43 op_sel_hi:[0,0,1]
	v_fma_mix_f32 v79, v57, s73, v42 op_sel:[0,0,1] op_sel_hi:[0,0,1]
	v_fma_mix_f32 v78, v57, s73, v42 op_sel_hi:[0,0,1]
	v_mul_f32_e32 v40, v78, v78
	v_mul_f32_e32 v68, v79, v79
	v_mul_f32_e32 v44, v70, v70
	v_mul_f32_e32 v46, v71, v71
	v_pk_add_f32 v[40:41], v[40:41], v[68:69]
	v_pk_add_f32 v[42:43], v[44:45], v[46:47]
	s_waitcnt vmcnt(4)
	v_cvt_f32_f16_sdwa v57, v33 dst_sel:DWORD dst_unused:UNUSED_PAD src0_sel:WORD_1
	v_pk_add_f32 v[40:41], v[40:41], v[42:43]
	s_nop 0
	v_add_f32_e32 v40, v40, v41
	s_nop 1
	v_mov_b32_dpp v41, v40 quad_perm:[1,0,3,2] row_mask:0xf bank_mask:0xf
	s_waitcnt lgkmcnt(0)
	v_add_f32_e32 v40, v40, v41
	s_nop 1
	v_mov_b32_dpp v41, v40 quad_perm:[2,3,0,1] row_mask:0xf bank_mask:0xf
	s_waitcnt lgkmcnt(0)
	v_add_f32_e32 v40, v40, v41
	s_nop 1
	v_mov_b32_dpp v41, v40 row_ror:4 row_mask:0xf bank_mask:0xf
	s_waitcnt lgkmcnt(0)
	v_add_f32_e32 v40, v40, v41
	s_nop 1
	v_mov_b32_dpp v41, v40 row_ror:8 row_mask:0xf bank_mask:0xf
	s_waitcnt lgkmcnt(0)
	v_add_f32_e32 v40, v40, v41
	ds_bpermute_b32 v41, v76, v40
	s_waitcnt lgkmcnt(0)
	v_add_f32_e32 v40, v40, v41
	ds_bpermute_b32 v41, v77, v40
	s_waitcnt lgkmcnt(0)
	v_add_f32_e32 v40, v40, v41
	v_fmamk_f32 v40, v40, 0x3a800000, v213
	v_cmp_gt_f32_e32 vcc, s52, v40
	v_mul_f32_e32 v41, 0x4f800000, v40
	s_nop 0
	v_cndmask_b32_e32 v40, v40, v41, vcc
	v_sqrt_f32_e32 v41, v40
	s_nop 0
	v_add_u32_e32 v42, -1, v41
	v_fma_f32 v43, -v42, v41, v40
	v_cmp_ge_f32_e64 s[10:11], 0, v43
	v_add_u32_e32 v43, 1, v41
	s_nop 0
	v_cndmask_b32_e64 v42, v41, v42, s[10:11]
	v_fma_f32 v41, -v43, v41, v40
	v_cmp_lt_f32_e64 s[10:11], 0, v41
	s_nop 1
	v_cndmask_b32_e64 v41, v42, v43, s[10:11]
	v_mul_f32_e32 v42, 0x37800000, v41
	v_cndmask_b32_e32 v41, v41, v42, vcc
	v_cmp_class_f32_e32 vcc, v40, v214
	s_nop 1
	v_cndmask_b32_e32 v40, v41, v40, vcc
	v_div_scale_f32 v41, s[10:11], v40, v40, 1.0
	v_rcp_f32_e32 v42, v41
	s_nop 0
	v_fma_f32 v43, -v41, v42, 1.0
	v_fmac_f32_e32 v42, v43, v42
	v_div_scale_f32 v43, vcc, 1.0, v40, 1.0
	v_mul_f32_e32 v44, v43, v42
	v_fma_f32 v45, -v41, v44, v43
	v_fmac_f32_e32 v44, v45, v42
	v_fma_f32 v41, -v41, v44, v43
	v_div_fmas_f32 v41, v41, v42, v44
	v_div_fixup_f32 v44, v41, v40, 1.0
	v_pk_mul_f32 v[40:41], v[48:49], v[44:45] op_sel_hi:[1,0]
	v_pk_mul_f32 v[42:43], v[50:51], v[44:45] op_sel_hi:[1,0]
	v_pk_fma_f32 v[48:49], v[4:5], v[40:41], v[12:13]
	v_pk_fma_f32 v[46:47], v[6:7], v[42:43], v[14:15]
	v_pk_mul_f32 v[40:41], v[52:53], v[44:45] op_sel_hi:[1,0]
	v_pk_mul_f32 v[42:43], v[54:55], v[44:45] op_sel_hi:[1,0]
	v_pk_fma_f32 v[40:41], v[0:1], v[40:41], v[8:9]
	v_pk_fma_f32 v[42:43], v[2:3], v[42:43], v[10:11]
	v_cvt_f32_f16_sdwa v51, v32 dst_sel:DWORD dst_unused:UNUSED_PAD src0_sel:WORD_1
	v_cvt_pk_f16_f32 v43, v42, v43
	v_cvt_pk_f16_f32 v42, v40, v41
	v_cvt_pk_f16_f32 v41, v46, v47
	v_cvt_pk_f16_f32 v40, v48, v49
	global_store_dwordx4 v[62:63], v[40:43], off
	v_cvt_f32_f16_e32 v55, v33
	v_cvt_f32_f16_sdwa v50, v34 dst_sel:DWORD dst_unused:UNUSED_PAD src0_sel:WORD_1
	v_pk_mul_f32 v[40:41], v[64:65], v[44:45] op_sel_hi:[1,0]
	v_pk_mul_f32 v[42:43], v[66:67], v[44:45] op_sel_hi:[1,0]
	v_pk_fma_f32 v[48:49], v[20:21], v[40:41], v[28:29]
	v_pk_fma_f32 v[46:47], v[22:23], v[42:43], v[30:31]
	v_pk_mul_f32 v[40:41], v[78:79], v[44:45] op_sel_hi:[1,0]
	v_pk_mul_f32 v[42:43], v[70:71], v[44:45] op_sel_hi:[1,0]
	v_pk_fma_f32 v[40:41], v[16:17], v[40:41], v[24:25]
	v_pk_fma_f32 v[42:43], v[18:19], v[42:43], v[26:27]
	v_cvt_f32_f16_e32 v44, v38
	v_cvt_pk_f16_f32 v43, v42, v43
	v_cvt_pk_f16_f32 v42, v40, v41
	v_cvt_pk_f16_f32 v41, v46, v47
	v_cvt_pk_f16_f32 v40, v48, v49
	global_store_dwordx4 v[62:63], v[40:43], off offset:1024
	v_cvt_f32_f16_sdwa v46, v38 dst_sel:DWORD dst_unused:UNUSED_PAD src0_sel:WORD_1
	v_cvt_f32_f16_e32 v45, v39
	v_cvt_f32_f16_e32 v40, v36
	v_cvt_f32_f16_sdwa v42, v36 dst_sel:DWORD dst_unused:UNUSED_PAD src0_sel:WORD_1
	v_cvt_f32_f16_e32 v41, v37
	v_cvt_f32_f16_sdwa v43, v37 dst_sel:DWORD dst_unused:UNUSED_PAD src0_sel:WORD_1
	v_cvt_f32_f16_sdwa v47, v39 dst_sel:DWORD dst_unused:UNUSED_PAD src0_sel:WORD_1
	v_cvt_f32_f16_e32 v49, v32
	v_cvt_f32_f16_e32 v48, v34
	v_pk_add_f32 v[40:41], v[40:41], v[42:43]
	v_cvt_f32_f16_sdwa v52, v35 dst_sel:DWORD dst_unused:UNUSED_PAD src0_sel:WORD_1
	v_cvt_f32_f16_e32 v54, v35
	v_add_f32_e32 v40, v40, v41
	v_add_f32_e32 v53, 0, v40
	v_pk_add_f32 v[40:41], v[44:45], v[46:47]
	v_add_f32_e32 v49, v49, v51
	v_pk_add_f32 v[40:41], v[40:41], v[40:41] op_sel_hi:[0,1]
	v_add_f32_e32 v51, v55, v57
	v_mov_b32_e32 v55, v41
	v_pk_add_f32 v[42:43], v[48:49], v[50:51]
	v_pk_add_f32 v[40:41], v[54:55], v[52:53]
	s_nop 0
	v_pk_add_f32 v[40:41], v[42:43], v[40:41]
	s_nop 0
	v_add_f32_e32 v40, v40, v41
	s_nop 1
	v_mov_b32_dpp v41, v40 quad_perm:[1,0,3,2] row_mask:0xf bank_mask:0xf
	s_waitcnt lgkmcnt(0)
; __device__ __forceinline__ void ln_pass(h16* Y16, const float* g, const float* b) {
;     ...
;     for (int row0 = (blockIdx.x * 8 + wave) * 4; row0 < NTOK; row0 += gridDim.x * 32) {
;     ...
;         for (int r = 0; r < 4; ++r) {
;             h16* yr = Y16 + (size_t)(row0 + r) * DM + 8 * lane; f32x4 v[4]; float s = 0.f;
; #pragma unroll
;             for (int j = 0; j < 2; ++j) {
;                 v[2 * j] = (f32x4){(float)w[r][j][0], (float)w[r][j][1], (float)w[r][j][2], (float)w[r][j][3]}; v[2 * j + 1] = (f32x4){(float)w[r][j][4], (float)w[r][j][5], (float)w[r][j][6], (float)w[r][j][7]}; }
; #pragma unroll
;             for (int j = 0; j < 4; ++j) s += (v[j].x + v[j].y) + (v[j].z + v[j].w);
;             const float mean = wave_sum(s) * (1.f / DM); float s2 = 0.f;
; #pragma unroll
;             for (int j = 0; j < 4; ++j) { v[j] = v[j] - mean; s2 += (v[j].x * v[j].x + v[j].y * v[j].y) + (v[j].z * v[j].z + v[j].w * v[j].w); }
;             const float rstd = 1.f / sqrtf(wave_sum(s2) * (1.f / DM) + LN_EPS);
; #pragma unroll
;             for (int j = 0; j < 2; ++j) { const f32x4 o0 = v[2 * j] * rstd * gv[2 * j] + bv[2 * j], o1 = v[2 * j + 1] * rstd * gv[2 * j + 1] + bv[2 * j + 1]; h16x8 o;
;                 o[0] = (h16)o0.x; o[1] = (h16)o0.y; o[2] = (h16)o0.z; o[3] = (h16)o0.w; o[4] = (h16)o1.x; o[5] = (h16)o1.y; o[6] = (h16)o1.z; o[7] = (h16)o1.w;
;                 *(h16x8*)(yr + 512 * j) = o; }
;         }
	v_add_f32_e32 v40, v40, v41
	s_nop 1
	v_mov_b32_dpp v41, v40 quad_perm:[2,3,0,1] row_mask:0xf bank_mask:0xf
	s_waitcnt lgkmcnt(0)
	v_add_f32_e32 v40, v40, v41
	s_nop 1
	v_mov_b32_dpp v41, v40 row_ror:4 row_mask:0xf bank_mask:0xf
	s_waitcnt lgkmcnt(0)
	v_add_f32_e32 v40, v40, v41
	s_nop 1
	v_mov_b32_dpp v41, v40 row_ror:8 row_mask:0xf bank_mask:0xf
	s_waitcnt lgkmcnt(0)
	v_add_f32_e32 v40, v40, v41
	ds_bpermute_b32 v41, v76, v40
	s_waitcnt lgkmcnt(0)
	v_add_f32_e32 v40, v40, v41
	ds_bpermute_b32 v41, v77, v40
	s_waitcnt lgkmcnt(0)
	v_add_f32_e32 v57, v40, v41
	v_fma_mix_f32 v41, v57, s73, v36 op_sel:[0,0,1] op_sel_hi:[0,0,1]
	v_fma_mix_f32 v40, v57, s73, v36 op_sel_hi:[0,0,1]
	v_fma_mix_f32 v43, v57, s73, v37 op_sel:[0,0,1] op_sel_hi:[0,0,1]
	v_fma_mix_f32 v42, v57, s73, v37 op_sel_hi:[0,0,1]
	v_pk_mul_f32 v[36:37], v[42:43], v[42:43]
	v_pk_mul_f32 v[44:45], v[40:41], v[40:41]
	v_fma_mix_f32 v55, v57, s73, v35 op_sel:[0,0,1] op_sel_hi:[0,0,1]
	v_pk_mov_b32 v[46:47], v[44:45], v[36:37] op_sel:[1,0]
	v_mov_b32_e32 v45, v37
	v_pk_add_f32 v[36:37], v[46:47], v[44:45]
	v_fma_mix_f32 v45, v57, s73, v38 op_sel:[0,0,1] op_sel_hi:[0,0,1]
	v_fma_mix_f32 v44, v57, s73, v38 op_sel_hi:[0,0,1]
	v_fma_mix_f32 v47, v57, s73, v39 op_sel:[0,0,1] op_sel_hi:[0,0,1]
	v_fma_mix_f32 v46, v57, s73, v39 op_sel_hi:[0,0,1]
	v_pk_mul_f32 v[38:39], v[46:47], v[46:47]
	v_pk_mul_f32 v[48:49], v[44:45], v[44:45]
	v_pk_add_f32 v[36:37], v[36:37], v[36:37] op_sel_hi:[0,1]
	v_pk_mov_b32 v[50:51], v[48:49], v[38:39] op_sel:[1,0]
	v_mov_b32_e32 v49, v39
	v_pk_add_f32 v[38:39], v[50:51], v[48:49]
	v_fma_mix_f32 v48, v57, s73, v32 op_sel_hi:[0,0,1]
	v_fma_mix_f32 v49, v57, s73, v32 op_sel:[0,0,1] op_sel_hi:[0,0,1]
	v_mul_f32_e32 v32, v48, v48
	v_fma_mix_f32 v51, v57, s73, v33 op_sel:[0,0,1] op_sel_hi:[0,0,1]
	v_fma_mix_f32 v50, v57, s73, v33 op_sel_hi:[0,0,1]
	v_pk_fma_f32 v[32:33], v[48:49], v[48:49], v[32:33] op_sel_hi:[1,1,0]
	v_pk_add_f32 v[38:39], v[38:39], v[38:39] op_sel_hi:[0,1]
	v_mul_f32_e32 v32, v50, v50
	v_pk_fma_f32 v[52:53], v[50:51], v[50:51], v[32:33] op_sel_hi:[1,1,0]
	v_fma_mix_f32 v54, v57, s73, v35 op_sel_hi:[0,0,1]
	v_fma_mix_f32 v63, v57, s73, v34 op_sel:[0,0,1] op_sel_hi:[0,0,1]
	v_fma_mix_f32 v62, v57, s73, v34 op_sel_hi:[0,0,1]
	v_mul_f32_e32 v32, v62, v62
	v_mul_f32_e32 v52, v63, v63
	v_mul_f32_e32 v36, v54, v54
	v_mul_f32_e32 v38, v55, v55
	v_pk_add_f32 v[32:33], v[32:33], v[52:53]
	v_pk_add_f32 v[34:35], v[36:37], v[38:39]
	s_nop 0
	v_pk_add_f32 v[32:33], v[32:33], v[34:35]
	s_nop 0
	v_add_f32_e32 v32, v32, v33
	s_nop 1
	v_mov_b32_dpp v33, v32 quad_perm:[1,0,3,2] row_mask:0xf bank_mask:0xf
	s_waitcnt lgkmcnt(0)
	v_add_f32_e32 v32, v32, v33
	s_nop 1
	v_mov_b32_dpp v33, v32 quad_perm:[2,3,0,1] row_mask:0xf bank_mask:0xf
	s_waitcnt lgkmcnt(0)
	v_add_f32_e32 v32, v32, v33
	s_nop 1
	v_mov_b32_dpp v33, v32 row_ror:4 row_mask:0xf bank_mask:0xf
	s_waitcnt lgkmcnt(0)
	v_add_f32_e32 v32, v32, v33
	s_nop 1
	v_mov_b32_dpp v33, v32 row_ror:8 row_mask:0xf bank_mask:0xf
	s_waitcnt lgkmcnt(0)
	v_add_f32_e32 v32, v32, v33
	ds_bpermute_b32 v33, v76, v32
	s_waitcnt lgkmcnt(0)
	v_add_f32_e32 v32, v32, v33
	ds_bpermute_b32 v33, v77, v32
	s_waitcnt lgkmcnt(0)
	v_add_f32_e32 v32, v32, v33
	v_fmamk_f32 v32, v32, 0x3a800000, v213
	v_cmp_gt_f32_e32 vcc, s52, v32
	v_mul_f32_e32 v33, 0x4f800000, v32
	s_nop 0
	v_cndmask_b32_e32 v32, v32, v33, vcc
	v_sqrt_f32_e32 v33, v32
	s_nop 0
	v_add_u32_e32 v34, -1, v33
	v_fma_f32 v35, -v34, v33, v32
	v_cmp_ge_f32_e64 s[10:11], 0, v35
	v_add_u32_e32 v35, 1, v33
	s_nop 0
	v_cndmask_b32_e64 v34, v33, v34, s[10:11]
	v_fma_f32 v33, -v35, v33, v32
	v_cmp_lt_f32_e64 s[10:11], 0, v33
	s_nop 1
	v_cndmask_b32_e64 v33, v34, v35, s[10:11]
	v_mul_f32_e32 v34, 0x37800000, v33
	v_cndmask_b32_e32 v33, v33, v34, vcc
	v_cmp_class_f32_e32 vcc, v32, v214
	s_nop 1
	v_cndmask_b32_e32 v32, v33, v32, vcc
	v_div_scale_f32 v33, s[10:11], v32, v32, 1.0
	v_rcp_f32_e32 v34, v33
	s_movk_i32 s10, 0x7fff
	v_fma_f32 v35, -v33, v34, 1.0
	v_fmac_f32_e32 v34, v35, v34
	v_div_scale_f32 v35, vcc, 1.0, v32, 1.0
	v_mul_f32_e32 v36, v35, v34
	v_fma_f32 v37, -v33, v36, v35
	v_fmac_f32_e32 v36, v37, v34
	v_fma_f32 v33, -v33, v36, v35
	v_div_fmas_f32 v33, v33, v34, v36
	v_div_fixup_f32 v36, v33, v32, 1.0
	v_pk_mul_f32 v[32:33], v[40:41], v[36:37] op_sel_hi:[1,0]
	v_pk_mul_f32 v[34:35], v[42:43], v[36:37] op_sel_hi:[1,0]
	v_pk_fma_f32 v[40:41], v[4:5], v[32:33], v[12:13]
	v_pk_fma_f32 v[38:39], v[6:7], v[34:35], v[14:15]
	v_pk_mul_f32 v[32:33], v[44:45], v[36:37] op_sel_hi:[1,0]
	v_pk_mul_f32 v[34:35], v[46:47], v[36:37] op_sel_hi:[1,0]
	v_pk_fma_f32 v[32:33], v[0:1], v[32:33], v[8:9]
	v_pk_fma_f32 v[34:35], v[2:3], v[34:35], v[10:11]
	v_cmp_lt_i32_e32 vcc, s10, v56
	v_cvt_pk_f16_f32 v35, v34, v35
	v_cvt_pk_f16_f32 v34, v32, v33
	v_cvt_pk_f16_f32 v33, v38, v39
	v_cvt_pk_f16_f32 v32, v40, v41
	global_store_dwordx4 v[60:61], v[32:35], off
	s_or_b64 s[4:5], vcc, s[4:5]
	s_nop 0
	v_pk_mul_f32 v[32:33], v[48:49], v[36:37] op_sel_hi:[1,0]
	v_pk_mul_f32 v[34:35], v[50:51], v[36:37] op_sel_hi:[1,0]
	v_pk_fma_f32 v[40:41], v[20:21], v[32:33], v[28:29]
	v_pk_fma_f32 v[38:39], v[22:23], v[34:35], v[30:31]
	v_pk_mul_f32 v[32:33], v[62:63], v[36:37] op_sel_hi:[1,0]
	v_pk_mul_f32 v[34:35], v[54:55], v[36:37] op_sel_hi:[1,0]
	v_pk_fma_f32 v[32:33], v[16:17], v[32:33], v[24:25]
	v_pk_fma_f32 v[34:35], v[18:19], v[34:35], v[26:27]
	s_nop 0
	v_cvt_pk_f16_f32 v35, v34, v35
	v_cvt_pk_f16_f32 v34, v32, v33
	v_cvt_pk_f16_f32 v33, v38, v39
	v_cvt_pk_f16_f32 v32, v40, v41
	global_store_dwordx4 v[60:61], v[32:35], off offset:1024
	s_andn2_b64 exec, exec, s[4:5]
	s_cbranch_execnz .LBB0_1063
